# PEER follower pacing: ahead threshold tightened from 0x280 to 0x200 expert ids, on top of v92
# speedup vs baseline: 1.0084x; 1.0084x over previous
.Lxp_chka:
	s_bitcmp1_b32 s2, 31
	s_cbranch_scc1 .Lxp_goa
	s_sub_i32 s3, s83, s2
	s_and_b32 s3, s3, 0x3fff
	s_cmp_lt_u32 s3, 0x2000
	s_cbranch_scc0 .Lxp_goa
	s_cmp_gt_u32 s3, 0x200
	s_cbranch_scc0 .Lxp_goa
	s_sub_i32 vcc_lo, vcc_lo, 1
	s_cmp_eq_u32 vcc_lo, 0
	s_cbranch_scc1 .Lxp_goa
	s_sleep 8
	global_load_dword v132, v[246:247], off sc1
	s_waitcnt vmcnt(0)
	v_readfirstlane_b32 s2, v132
	s_branch .Lxp_chka
